# MLP-in GEMM: per-row scale loads hoisted from the epilogue to tile start (spare VGPRs), epilogue vmcnt(0) drain removed; placement of later phases kept
# baseline (speedup 1.0000x reference)
; #define PG8_STAGE(bufoff, gbase, voff) do { _Pragma("unroll") for (int _i = 0; _i < 2; ++_i) \
;         __builtin_amdgcn_global_load_lds((const unsigned*)((const char*)(gbase) + (voff)[_i]), (PG8_LAS unsigned*)(lds + (bufoff) + ldsw + _i * 8192), 16, 0, 0); } while (0)
; #define PG8_LDA(dst, b, h) do { _Pragma("unroll") for (int m = 0; m < 4; ++m) _Pragma("unroll") for (int k = 0; k < 2; ++k) dst[m][k] = *(const PG8_LAS bf16x8*)(lds + PG8_SA(b, h) + aoff + m * 2048 + k * 1024); } while (0)
; #define PG8_WAIT_V(n) asm volatile("s_waitcnt vmcnt(" #n ")" ::: "memory")
; #define PG8_BAR __builtin_amdgcn_s_barrier()
;     __device__ __forceinline__ void operator()(const f32x4 (&acc)[2][2][4][2], const Unit& u, int wr, int wc, int fr, int fq) const {
;     ...
;         const int row0 = u.pm * BM + wr * 64 + fr; const int col0 = u.pn * BM + wc * 32 + 8 * fq;
;         float scr[8];
; #pragma unroll
;         for (int gi = 0; gi < 8; ++gi) scr[gi] = RS ? rs[row0 + (gi >> 2) * HALF + (gi & 3) * 16] : 1.f;
; template <class Epi, class Sched, bool ALIGN_EPI = false, bool SP2 = false>
; __device__ __forceinline__ void gemm_phase(PG8_LAS unsigned char* lds, const Gemm g, const Sched& S, const Epi& E, const int tid) {
;     ...
;         const bool has_next = S.next(ui + 1, nxt);
;         const char* nA = has_next ? (const char*)g.A + (size_t)nxt.pm * tstep : cA; const char* nB = has_next ? (const char*)g.Bt + (size_t)nxt.pn * tstep : cB;
;         for (int t = 0; t < nt; t += 2) {
;             const bool last = (t == nt - 2);
;             const char* a1 = cA + (size_t)(t + 1) * kstep;
;             const char* a2 = last ? nA : cA + (size_t)(t + 2) * kstep; const char* b2 = last ? nB : cB + (size_t)(t + 2) * kstep;
;             const char* a3 = a2 + kstep; const char* b3 = b2 + kstep;
;             if (last && has_next) S.a_ready(nxt);
;             if constexpr (SP2) {
;             PG8_LDB(B0, 0, 0); PG8_LDB(B1, 0, 1); PG8_SCHED; PG8_LDA(At, 0, 0); PG8_STAGE(PG8_SA(1, 1), a1 + hstep, voffA);
;             PG8_WAIT_V(8); PG8_WAIT_L(0); PG8_BAR; PG8_MMA(0, 0, At, B0); PG8_MMA(0, 1, At, B1); PG8_BAR; PG8_SCHED;
;             PG8_LDA(At, 0, 1); PG8_STAGE(PG8_SB(0, 0), b2, voffB); PG8_STAGE(PG8_SB(0, 1), b2 + hstep, voffB); PG8_STAGE(PG8_SA(0, 0), a2, voffA);
;             PG8_WAIT_V(8); PG8_WAIT_L(0); PG8_BAR; PG8_MMA(1, 0, At, B0); PG8_MMA(1, 1, At, B1); PG8_BAR; PG8_SCHED;
.LBB0_1087:
	s_ashr_i32 s19, s18, 31
	s_lshl_b64 s[20:21], s[18:19], 20
	s_add_u32 s20, s11, s20
	s_addc_u32 s21, s33, s21
	s_and_b64 s[22:23], s[4:5], exec
	s_cselect_b32 s19, s21, s27
	s_cselect_b32 s50, s20, s26
	s_ashr_i32 s17, s16, 31
	s_lshl_b64 s[22:23], s[16:17], 20
	s_add_u32 s22, s34, s22
	s_addc_u32 s23, s35, s23
	s_and_b64 s[30:31], s[4:5], exec
	s_cselect_b32 s17, s23, s29
	s_cselect_b32 s51, s22, s28
	s_add_u32 s26, s26, 0x80080
	s_addc_u32 s27, s27, 0
	s_add_u32 s52, s28, 0x100
	s_addc_u32 s53, s29, 0
	s_mov_b32 s54, -2
	s_nop 0
	s_nop 0
	s_nop 0
	s_nop 0
	s_nop 0
	s_lshl_b32 s100, s24, 8
	s_add_i32 s100, s100, s44
	v_mbcnt_lo_u32_b32 v246, -1, 0
	v_mbcnt_hi_u32_b32 v246, -1, v246
	s_nop 0
	v_and_or_b32 v246, v246, 15, s100
	v_ashrrev_i32_e32 v247, 31, v246
	v_lshl_add_u64 v[246:247], v[246:247], 2, s[12:13]
	global_load_dword v220, v[246:247], off
	global_load_dword v228, v[246:247], off offset:64
	global_load_dword v230, v[246:247], off offset:128
	global_load_dword v232, v[246:247], off offset:192
	global_load_dword v236, v[246:247], off offset:512
	global_load_dword v240, v[246:247], off offset:576
	global_load_dword v242, v[246:247], off offset:640
	global_load_dword v244, v[246:247], off offset:704
	s_add_i32 s55, 0, 0x10000
	v_add_u32_e32 v138, s55, v139
	s_add_i32 s62, 0, 0x14000
	ds_read_b128 v[144:147], v138
	ds_read_b128 v[148:151], v138 offset:1024
	ds_read_b128 v[152:155], v138 offset:2048
	ds_read_b128 v[156:159], v138 offset:3072
	v_add_u32_e32 v138, s62, v139
	ds_read_b128 v[160:163], v138
	ds_read_b128 v[164:167], v138 offset:1024
	ds_read_b128 v[168:171], v138 offset:2048
	ds_read_b128 v[172:175], v138 offset:3072
	v_lshl_add_u64 v[140:141], s[26:27], 0, v[134:135]
	s_add_i32 m0, s37, 0xc000
	ds_read_b128 v[176:179], v143
	ds_read_b128 v[180:183], v143 offset:1024
	ds_read_b128 v[184:187], v143 offset:2048
	ds_read_b128 v[188:191], v143 offset:3072
	ds_read_b128 v[192:195], v143 offset:4096
	ds_read_b128 v[196:199], v143 offset:5120
	ds_read_b128 v[200:203], v143 offset:6144
	ds_read_b128 v[206:209], v143 offset:7168
	s_add_u32 s28, s26, 0xfff80080
	s_addc_u32 s29, s27, -1
	s_cmp_eq_u32 s54, 28
	s_cselect_b32 s31, s19, s29
	s_cselect_b32 s30, s50, s28
	s_cselect_b32 s29, s17, s53
	s_cselect_b32 s28, s51, s52
	global_load_lds_dwordx4 v[140:141], off
	v_lshl_add_u64 v[140:141], s[26:27], 0, v[136:137]
	s_add_i32 m0, s37, 0xe000
	s_nop 0
	global_load_lds_dwordx4 v[140:141], off
	s_waitcnt vmcnt(32)
	s_waitcnt lgkmcnt(0)
	s_setprio 1
	s_barrier
	v_mfma_f32_16x16x32_bf16 v[124:127], v[144:147], v[176:179], 0
	v_mfma_f32_16x16x32_bf16 v[120:123], v[152:155], v[176:179], 0
	v_mfma_f32_16x16x32_bf16 v[108:111], v[144:147], v[184:187], 0
	v_mfma_f32_16x16x32_bf16 v[104:107], v[152:155], v[184:187], 0
	v_mfma_f32_16x16x32_bf16 v[92:95], v[144:147], v[192:195], 0
	v_mfma_f32_16x16x32_bf16 v[88:91], v[152:155], v[192:195], 0
	v_mfma_f32_16x16x32_bf16 v[76:79], v[144:147], v[200:203], 0
	v_mfma_f32_16x16x32_bf16 v[72:75], v[152:155], v[200:203], 0
	v_mfma_f32_16x16x32_bf16 v[124:127], v[148:151], v[180:183], v[124:127]
	v_mfma_f32_16x16x32_bf16 v[120:123], v[156:159], v[180:183], v[120:123]
	v_mfma_f32_16x16x32_bf16 v[108:111], v[148:151], v[188:191], v[108:111]
	v_mfma_f32_16x16x32_bf16 v[104:107], v[156:159], v[188:191], v[104:107]
	v_mfma_f32_16x16x32_bf16 v[92:95], v[148:151], v[196:199], v[92:95]
	v_mfma_f32_16x16x32_bf16 v[88:91], v[156:159], v[196:199], v[88:91]
	v_mfma_f32_16x16x32_bf16 v[76:79], v[148:151], v[206:209], v[76:79]
	v_mfma_f32_16x16x32_bf16 v[72:75], v[156:159], v[206:209], v[72:75]
	s_setprio 0
	s_setprio 1
	v_mfma_f32_16x16x32_bf16 v[116:119], v[160:163], v[176:179], 0
	v_mfma_f32_16x16x32_bf16 v[112:115], v[168:171], v[176:179], 0
	v_mfma_f32_16x16x32_bf16 v[100:103], v[160:163], v[184:187], 0
	v_mfma_f32_16x16x32_bf16 v[96:99], v[168:171], v[184:187], 0
	v_mfma_f32_16x16x32_bf16 v[84:87], v[160:163], v[192:195], 0
	v_mfma_f32_16x16x32_bf16 v[80:83], v[168:171], v[192:195], 0
	v_mfma_f32_16x16x32_bf16 v[68:71], v[160:163], v[200:203], 0
	v_mfma_f32_16x16x32_bf16 v[64:67], v[168:171], v[200:203], 0
	v_mfma_f32_16x16x32_bf16 v[116:119], v[164:167], v[180:183], v[116:119]
	v_mfma_f32_16x16x32_bf16 v[112:115], v[172:175], v[180:183], v[112:115]
	v_mfma_f32_16x16x32_bf16 v[100:103], v[164:167], v[188:191], v[100:103]
	v_mfma_f32_16x16x32_bf16 v[96:99], v[172:175], v[188:191], v[96:99]
	v_mfma_f32_16x16x32_bf16 v[84:87], v[164:167], v[196:199], v[84:87]
	v_mfma_f32_16x16x32_bf16 v[80:83], v[172:175], v[196:199], v[80:83]
	v_mfma_f32_16x16x32_bf16 v[68:71], v[164:167], v[206:209], v[68:71]
	v_mfma_f32_16x16x32_bf16 v[64:67], v[172:175], v[206:209], v[64:67]
	s_barrier
	s_setprio 0
	s_add_i32 s55, s55, s36
	v_lshl_add_u64 v[140:141], s[28:29], 0, v[204:205]
	s_mov_b32 m0, s55
	ds_read_b128 v[176:179], v143 offset:16384
	ds_read_b128 v[180:183], v143 offset:17408
	ds_read_b128 v[184:187], v143 offset:18432
	ds_read_b128 v[188:191], v143 offset:19456
	ds_read_b128 v[192:195], v143 offset:20480
	ds_read_b128 v[196:199], v143 offset:21504
	ds_read_b128 v[200:203], v143 offset:22528
	ds_read_b128 v[206:209], v143 offset:23552
	global_load_lds_dwordx4 v[140:141], off
	s_add_i32 m0, s55, 0x2000
	s_add_u32 s64, s28, 0x80000
	v_lshl_add_u64 v[210:211], s[28:29], 0, v[132:133]
	s_addc_u32 s65, s29, 0
	s_add_i32 s55, s62, s36
	global_load_lds_dwordx4 v[210:211], off
	v_lshl_add_u64 v[212:213], s[64:65], 0, v[204:205]
	s_mov_b32 m0, s55
	v_lshl_add_u64 v[214:215], s[30:31], 0, v[130:131]
	global_load_lds_dwordx4 v[212:213], off
	v_lshl_add_u64 v[212:213], s[64:65], 0, v[132:133]
	s_add_i32 m0, s55, 0x2000
	s_nop 0
	global_load_lds_dwordx4 v[212:213], off
	v_lshl_add_u64 v[212:213], s[30:31], 0, v[128:129]
	s_mov_b32 m0, s37
	s_nop 0
	global_load_lds_dwordx4 v[212:213], off
	s_mov_b32 m0, s38
	s_nop 0
	global_load_lds_dwordx4 v[214:215], off
	s_waitcnt vmcnt(16)
	s_waitcnt lgkmcnt(0)
	s_setprio 1
	s_barrier
; #define PG8_STAGE(bufoff, gbase, voff) do { _Pragma("unroll") for (int _i = 0; _i < 2; ++_i) \
;         __builtin_amdgcn_global_load_lds((const unsigned*)((const char*)(gbase) + (voff)[_i]), (PG8_LAS unsigned*)(lds + (bufoff) + ldsw + _i * 8192), 16, 0, 0); } while (0)
; #define PG8_LDA(dst, b, h) do { _Pragma("unroll") for (int m = 0; m < 4; ++m) _Pragma("unroll") for (int k = 0; k < 2; ++k) dst[m][k] = *(const PG8_LAS bf16x8*)(lds + PG8_SA(b, h) + aoff + m * 2048 + k * 1024); } while (0)
; #define PG8_LDB(dst, b, h) do { _Pragma("unroll") for (int n = 0; n < 2; ++n) _Pragma("unroll") for (int k = 0; k < 2; ++k) dst[n][k] = *(const PG8_LAS bf16x8*)(lds + PG8_SB(b, h) + boff + n * 2048 + k * 1024); } while (0)
; #define PG8_MMA(ai, bj, At, Bt) do { __builtin_amdgcn_s_setprio(1); _Pragma("unroll") for (int m = 0; m < 4; ++m) _Pragma("unroll") for (int n = 0; n < 2; ++n) _Pragma("unroll") for (int k = 0; k < 2; ++k) \
;         acc[ai][bj][m][n] = __builtin_amdgcn_mfma_f32_16x16x32_bf16(Bt[n][k], At[m][k], acc[ai][bj][m][n], 0, 0, 0); __builtin_amdgcn_s_setprio(0); } while (0)
; #define PG8_WAIT_V(n) asm volatile("s_waitcnt vmcnt(" #n ")" ::: "memory")
; #define PG8_WAIT_L(n) asm volatile("s_waitcnt lgkmcnt(" #n ")" ::: "memory")
; #define PG8_BAR __builtin_amdgcn_s_barrier()
; #define PG8_SCHED __builtin_amdgcn_sched_barrier(0)
; template <class Epi, class Sched, bool ALIGN_EPI = false, bool SP2 = false>
; __device__ __forceinline__ void gemm_phase(PG8_LAS unsigned char* lds, const Gemm g, const Sched& S, const Epi& E, const int tid) {
;     ...
;             PG8_LDA(At, 0, 1); PG8_STAGE(PG8_SB(0, 0), b2, voffB); PG8_STAGE(PG8_SB(0, 1), b2 + hstep, voffB); PG8_STAGE(PG8_SA(0, 0), a2, voffA);
;             PG8_WAIT_V(8); PG8_WAIT_L(0); PG8_BAR; PG8_MMA(1, 0, At, B0); PG8_MMA(1, 1, At, B1); PG8_BAR; PG8_SCHED;
;             PG8_LDB(B0, 1, 0); PG8_LDB(B1, 1, 1); PG8_SCHED; PG8_LDA(At, 1, 0); PG8_STAGE(PG8_SA(0, 1), a2 + hstep, voffA);
;             PG8_WAIT_V(8); PG8_WAIT_L(0); PG8_BAR; PG8_MMA(0, 0, At, B0); PG8_MMA(0, 1, At, B1); PG8_BAR; PG8_SCHED;
	v_mfma_f32_16x16x32_bf16 v[60:63], v[144:147], v[176:179], 0
	v_mfma_f32_16x16x32_bf16 v[56:59], v[152:155], v[176:179], 0
	v_mfma_f32_16x16x32_bf16 v[44:47], v[144:147], v[184:187], 0
	v_mfma_f32_16x16x32_bf16 v[40:43], v[152:155], v[184:187], 0
	v_mfma_f32_16x16x32_bf16 v[28:31], v[144:147], v[192:195], 0
	v_mfma_f32_16x16x32_bf16 v[24:27], v[152:155], v[192:195], 0
	v_mfma_f32_16x16x32_bf16 v[12:15], v[144:147], v[200:203], 0
	v_mfma_f32_16x16x32_bf16 v[8:11], v[152:155], v[200:203], 0
	v_mfma_f32_16x16x32_bf16 v[60:63], v[148:151], v[180:183], v[60:63]
	v_mfma_f32_16x16x32_bf16 v[56:59], v[156:159], v[180:183], v[56:59]
	v_mfma_f32_16x16x32_bf16 v[44:47], v[148:151], v[188:191], v[44:47]
	v_mfma_f32_16x16x32_bf16 v[40:43], v[156:159], v[188:191], v[40:43]
	v_mfma_f32_16x16x32_bf16 v[28:31], v[148:151], v[196:199], v[28:31]
	v_mfma_f32_16x16x32_bf16 v[24:27], v[156:159], v[196:199], v[24:27]
	v_mfma_f32_16x16x32_bf16 v[12:15], v[148:151], v[206:209], v[12:15]
	v_mfma_f32_16x16x32_bf16 v[8:11], v[156:159], v[206:209], v[8:11]
	s_setprio 0
	s_setprio 1
	v_mfma_f32_16x16x32_bf16 v[52:55], v[160:163], v[176:179], 0
	v_mfma_f32_16x16x32_bf16 v[48:51], v[168:171], v[176:179], 0
	v_mfma_f32_16x16x32_bf16 v[36:39], v[160:163], v[184:187], 0
	v_mfma_f32_16x16x32_bf16 v[32:35], v[168:171], v[184:187], 0
	v_mfma_f32_16x16x32_bf16 v[20:23], v[160:163], v[192:195], 0
	v_mfma_f32_16x16x32_bf16 v[16:19], v[168:171], v[192:195], 0
	v_mfma_f32_16x16x32_bf16 v[4:7], v[160:163], v[200:203], 0
	v_mfma_f32_16x16x32_bf16 v[0:3], v[168:171], v[200:203], 0
	v_mfma_f32_16x16x32_bf16 v[52:55], v[164:167], v[180:183], v[52:55]
	v_mfma_f32_16x16x32_bf16 v[48:51], v[172:175], v[180:183], v[48:51]
	v_mfma_f32_16x16x32_bf16 v[36:39], v[164:167], v[188:191], v[36:39]
	v_mfma_f32_16x16x32_bf16 v[32:35], v[172:175], v[188:191], v[32:35]
	v_mfma_f32_16x16x32_bf16 v[20:23], v[164:167], v[196:199], v[20:23]
	v_mfma_f32_16x16x32_bf16 v[16:19], v[172:175], v[196:199], v[16:19]
	v_mfma_f32_16x16x32_bf16 v[4:7], v[164:167], v[206:209], v[4:7]
	v_mfma_f32_16x16x32_bf16 v[0:3], v[172:175], v[206:209], v[0:3]
	s_barrier
	s_setprio 0
	s_add_i32 s55, 0, 0x18000
	v_add_u32_e32 v138, s55, v139
	s_add_i32 s62, 0, 0x1c000
	ds_read_b128 v[144:147], v138
	ds_read_b128 v[148:151], v138 offset:1024
	ds_read_b128 v[152:155], v138 offset:2048
	ds_read_b128 v[156:159], v138 offset:3072
	v_add_u32_e32 v138, s62, v139
	ds_read_b128 v[160:163], v138
	ds_read_b128 v[164:167], v138 offset:1024
	ds_read_b128 v[168:171], v138 offset:2048
	ds_read_b128 v[172:175], v138 offset:3072
	s_add_u32 s30, s30, 0x80000
	s_addc_u32 s31, s31, 0
	s_mov_b32 m0, s40
	v_lshl_add_u64 v[216:217], s[30:31], 0, v[128:129]
	ds_read_b128 v[176:179], v143 offset:32768
	ds_read_b128 v[180:183], v143 offset:33792
	ds_read_b128 v[184:187], v143 offset:34816
	ds_read_b128 v[188:191], v143 offset:35840
	ds_read_b128 v[192:195], v143 offset:36864
	ds_read_b128 v[196:199], v143 offset:37888
	ds_read_b128 v[200:203], v143 offset:38912
	ds_read_b128 v[206:209], v143 offset:39936
	global_load_lds_dwordx4 v[216:217], off
	v_lshl_add_u64 v[216:217], s[30:31], 0, v[130:131]
	s_mov_b32 m0, s42
	s_nop 0
	global_load_lds_dwordx4 v[216:217], off
	s_waitcnt vmcnt(8)
	s_waitcnt lgkmcnt(0)
	s_setprio 1
	s_barrier
	v_mfma_f32_16x16x32_bf16 v[124:127], v[144:147], v[176:179], v[124:127]
	v_mfma_f32_16x16x32_bf16 v[120:123], v[152:155], v[176:179], v[120:123]
	v_mfma_f32_16x16x32_bf16 v[108:111], v[144:147], v[184:187], v[108:111]
	v_mfma_f32_16x16x32_bf16 v[104:107], v[152:155], v[184:187], v[104:107]
	v_mfma_f32_16x16x32_bf16 v[92:95], v[144:147], v[192:195], v[92:95]
	v_mfma_f32_16x16x32_bf16 v[88:91], v[152:155], v[192:195], v[88:91]
	v_mfma_f32_16x16x32_bf16 v[76:79], v[144:147], v[200:203], v[76:79]
	v_mfma_f32_16x16x32_bf16 v[72:75], v[152:155], v[200:203], v[72:75]
	v_mfma_f32_16x16x32_bf16 v[124:127], v[148:151], v[180:183], v[124:127]
	v_mfma_f32_16x16x32_bf16 v[120:123], v[156:159], v[180:183], v[120:123]
	v_mfma_f32_16x16x32_bf16 v[108:111], v[148:151], v[188:191], v[108:111]
	v_mfma_f32_16x16x32_bf16 v[104:107], v[156:159], v[188:191], v[104:107]
	v_mfma_f32_16x16x32_bf16 v[92:95], v[148:151], v[196:199], v[92:95]
	v_mfma_f32_16x16x32_bf16 v[88:91], v[156:159], v[196:199], v[88:91]
	v_mfma_f32_16x16x32_bf16 v[76:79], v[148:151], v[206:209], v[76:79]
	v_mfma_f32_16x16x32_bf16 v[72:75], v[156:159], v[206:209], v[72:75]
	s_setprio 0
	s_setprio 1
	v_mfma_f32_16x16x32_bf16 v[116:119], v[160:163], v[176:179], v[116:119]
	v_mfma_f32_16x16x32_bf16 v[112:115], v[168:171], v[176:179], v[112:115]
	v_mfma_f32_16x16x32_bf16 v[100:103], v[160:163], v[184:187], v[100:103]
	v_mfma_f32_16x16x32_bf16 v[96:99], v[168:171], v[184:187], v[96:99]
	v_mfma_f32_16x16x32_bf16 v[84:87], v[160:163], v[192:195], v[84:87]
	v_mfma_f32_16x16x32_bf16 v[80:83], v[168:171], v[192:195], v[80:83]
	v_mfma_f32_16x16x32_bf16 v[68:71], v[160:163], v[200:203], v[68:71]
	v_mfma_f32_16x16x32_bf16 v[64:67], v[168:171], v[200:203], v[64:67]
	v_mfma_f32_16x16x32_bf16 v[116:119], v[164:167], v[180:183], v[116:119]
	v_mfma_f32_16x16x32_bf16 v[112:115], v[172:175], v[180:183], v[112:115]
	v_mfma_f32_16x16x32_bf16 v[100:103], v[164:167], v[188:191], v[100:103]
	v_mfma_f32_16x16x32_bf16 v[96:99], v[172:175], v[188:191], v[96:99]
	v_mfma_f32_16x16x32_bf16 v[84:87], v[164:167], v[196:199], v[84:87]
	v_mfma_f32_16x16x32_bf16 v[80:83], v[172:175], v[196:199], v[80:83]
	v_mfma_f32_16x16x32_bf16 v[68:71], v[164:167], v[206:209], v[68:71]
	v_mfma_f32_16x16x32_bf16 v[64:67], v[172:175], v[206:209], v[64:67]
	s_barrier
; #define PG8_STAGE(bufoff, gbase, voff) do { _Pragma("unroll") for (int _i = 0; _i < 2; ++_i) \
;         __builtin_amdgcn_global_load_lds((const unsigned*)((const char*)(gbase) + (voff)[_i]), (PG8_LAS unsigned*)(lds + (bufoff) + ldsw + _i * 8192), 16, 0, 0); } while (0)
; #define PG8_LDA(dst, b, h) do { _Pragma("unroll") for (int m = 0; m < 4; ++m) _Pragma("unroll") for (int k = 0; k < 2; ++k) dst[m][k] = *(const PG8_LAS bf16x8*)(lds + PG8_SA(b, h) + aoff + m * 2048 + k * 1024); } while (0)
; #define PG8_MMA(ai, bj, At, Bt) do { __builtin_amdgcn_s_setprio(1); _Pragma("unroll") for (int m = 0; m < 4; ++m) _Pragma("unroll") for (int n = 0; n < 2; ++n) _Pragma("unroll") for (int k = 0; k < 2; ++k) \
;         acc[ai][bj][m][n] = __builtin_amdgcn_mfma_f32_16x16x32_bf16(Bt[n][k], At[m][k], acc[ai][bj][m][n], 0, 0, 0); __builtin_amdgcn_s_setprio(0); } while (0)
; #define PG8_WAIT_V(n) asm volatile("s_waitcnt vmcnt(" #n ")" ::: "memory")
; #define PG8_WAIT_L(n) asm volatile("s_waitcnt lgkmcnt(" #n ")" ::: "memory")
; #define PG8_BAR __builtin_amdgcn_s_barrier()
; #define PG8_SCHED __builtin_amdgcn_sched_barrier(0)
; template <class Epi, class Sched, bool ALIGN_EPI = false, bool SP2 = false>
; __device__ __forceinline__ void gemm_phase(PG8_LAS unsigned char* lds, const Gemm g, const Sched& S, const Epi& E, const int tid) {
;     ...
;             PG8_LDA(At, 1, 1); PG8_STAGE(PG8_SB(1, 0), b3, voffB); PG8_STAGE(PG8_SB(1, 1), b3 + hstep, voffB); PG8_STAGE(PG8_SA(1, 0), a3, voffA);
;             PG8_WAIT_V(8); PG8_WAIT_L(0); PG8_BAR; PG8_MMA(1, 0, At, B0); PG8_MMA(1, 1, At, B1); PG8_BAR; PG8_SCHED;
	s_setprio 0
	s_add_i32 s30, s55, s36
	v_lshl_add_u64 v[140:141], v[140:141], 0, s[70:71]
	s_mov_b32 m0, s30
	ds_read_b128 v[176:179], v143 offset:49152
	ds_read_b128 v[180:183], v143 offset:50176
	ds_read_b128 v[184:187], v143 offset:51200
	ds_read_b128 v[188:191], v143 offset:52224
	ds_read_b128 v[192:195], v143 offset:53248
	ds_read_b128 v[196:199], v143 offset:54272
	ds_read_b128 v[200:203], v143 offset:55296
	ds_read_b128 v[206:209], v143 offset:56320
	global_load_lds_dwordx4 v[140:141], off
	s_add_i32 m0, s30, 0x2000
	s_add_u32 s28, s28, 0x80080
	v_lshl_add_u64 v[140:141], v[210:211], 0, s[70:71]
	s_addc_u32 s29, s29, 0
	s_add_i32 s30, s62, s36
	global_load_lds_dwordx4 v[140:141], off
	v_lshl_add_u64 v[140:141], s[28:29], 0, v[204:205]
	s_mov_b32 m0, s30
	s_nop 0
	global_load_lds_dwordx4 v[140:141], off
	v_lshl_add_u64 v[140:141], s[28:29], 0, v[132:133]
	s_add_i32 m0, s30, 0x2000
	s_nop 0
	global_load_lds_dwordx4 v[140:141], off
	v_lshl_add_u64 v[140:141], v[212:213], 0, s[70:71]
	s_mov_b32 m0, s46
	s_nop 0
	global_load_lds_dwordx4 v[140:141], off
	v_lshl_add_u64 v[140:141], v[214:215], 0, s[70:71]
	s_mov_b32 m0, s47
	s_nop 0
	global_load_lds_dwordx4 v[140:141], off
	s_add_i32 s54, s54, 2
	s_add_u32 s26, s26, 0x100
	s_addc_u32 s27, s27, 0
	s_add_u32 s52, s52, 0x100
	s_addc_u32 s53, s53, 0
	s_waitcnt vmcnt(8)
	s_waitcnt lgkmcnt(0)
	s_setprio 1
	s_barrier
	v_mfma_f32_16x16x32_bf16 v[60:63], v[144:147], v[176:179], v[60:63]
	v_mfma_f32_16x16x32_bf16 v[56:59], v[152:155], v[176:179], v[56:59]
	v_mfma_f32_16x16x32_bf16 v[44:47], v[144:147], v[184:187], v[44:47]
	v_mfma_f32_16x16x32_bf16 v[40:43], v[152:155], v[184:187], v[40:43]
	v_mfma_f32_16x16x32_bf16 v[28:31], v[144:147], v[192:195], v[28:31]
	v_mfma_f32_16x16x32_bf16 v[24:27], v[152:155], v[192:195], v[24:27]
	v_mfma_f32_16x16x32_bf16 v[12:15], v[144:147], v[200:203], v[12:15]
	v_mfma_f32_16x16x32_bf16 v[8:11], v[152:155], v[200:203], v[8:11]
	v_mfma_f32_16x16x32_bf16 v[60:63], v[148:151], v[180:183], v[60:63]
	v_mfma_f32_16x16x32_bf16 v[56:59], v[156:159], v[180:183], v[56:59]
	v_mfma_f32_16x16x32_bf16 v[44:47], v[148:151], v[188:191], v[44:47]
	v_mfma_f32_16x16x32_bf16 v[40:43], v[156:159], v[188:191], v[40:43]
	v_mfma_f32_16x16x32_bf16 v[28:31], v[148:151], v[196:199], v[28:31]
	v_mfma_f32_16x16x32_bf16 v[24:27], v[156:159], v[196:199], v[24:27]
	v_mfma_f32_16x16x32_bf16 v[12:15], v[148:151], v[206:209], v[12:15]
	v_mfma_f32_16x16x32_bf16 v[8:11], v[156:159], v[206:209], v[8:11]
	s_setprio 0
	s_setprio 1
	v_mfma_f32_16x16x32_bf16 v[52:55], v[160:163], v[176:179], v[52:55]
	v_mfma_f32_16x16x32_bf16 v[48:51], v[168:171], v[176:179], v[48:51]
	v_mfma_f32_16x16x32_bf16 v[36:39], v[160:163], v[184:187], v[36:39]
	v_mfma_f32_16x16x32_bf16 v[32:35], v[168:171], v[184:187], v[32:35]
	v_mfma_f32_16x16x32_bf16 v[20:23], v[160:163], v[192:195], v[20:23]
	v_mfma_f32_16x16x32_bf16 v[16:19], v[168:171], v[192:195], v[16:19]
	v_mfma_f32_16x16x32_bf16 v[4:7], v[160:163], v[200:203], v[4:7]
	v_mfma_f32_16x16x32_bf16 v[0:3], v[168:171], v[200:203], v[0:3]
	v_mfma_f32_16x16x32_bf16 v[52:55], v[164:167], v[180:183], v[52:55]
	v_mfma_f32_16x16x32_bf16 v[48:51], v[172:175], v[180:183], v[48:51]
	v_mfma_f32_16x16x32_bf16 v[36:39], v[164:167], v[188:191], v[36:39]
	v_mfma_f32_16x16x32_bf16 v[32:35], v[172:175], v[188:191], v[32:35]
	v_mfma_f32_16x16x32_bf16 v[20:23], v[164:167], v[196:199], v[20:23]
	v_mfma_f32_16x16x32_bf16 v[16:19], v[172:175], v[196:199], v[16:19]
	v_mfma_f32_16x16x32_bf16 v[4:7], v[164:167], v[206:209], v[4:7]
	v_mfma_f32_16x16x32_bf16 v[0:3], v[172:175], v[206:209], v[0:3]
	s_barrier
	s_setprio 0

; __device__ __forceinline__ unsigned cvt_pk_bf16(float lo, float hi) { unsigned r; asm volatile("v_cvt_pk_bf16_f32 %0, %1, %2" : "=v"(r) : "v"(lo), "v"(hi)); return r; }
;     __device__ __forceinline__ void operator()(const f32x4 (&acc)[2][2][4][2], const Unit& u, int wr, int wc, int fr, int fq) const {
;     ...
;         const int row0 = u.pm * BM + wr * 64 + fr; const int col0 = u.pn * BM + wc * 32 + 8 * fq;
;         float scr[8];
; #pragma unroll
;         for (int gi = 0; gi < 8; ++gi) scr[gi] = RS ? rs[row0 + (gi >> 2) * HALF + (gi & 3) * 16] : 1.f;
; #pragma unroll
;         for (int ai = 0; ai < 2; ++ai)
; #pragma unroll
;             for (int m = 0; m < 4; ++m) { const int row = row0 + ai * HALF + m * 16; bf16_t* rowp = O + (size_t)row * ldc + col0;
;                 const float sc = scr[ai * 4 + m];
;                 float q = 0.f;
; #pragma unroll
;                 for (int bj = 0; bj < 2; ++bj) { f32x4 v0 = acc[ai][bj][m][0], v1 = acc[ai][bj][m][1];
;                     if (RS) { v0 = v0 * sc; v1 = v1 * sc; }
;                     if (ACT == 1) {
; #pragma unroll
;                         for (int j = 0; j < 4; ++j) { const float a = fmaxf(v0[j], 0.f), b = fmaxf(v1[j], 0.f); v0[j] = a * a; v1[j] = b * b; } }
;                     if (SS) {
; #pragma unroll
;                         for (int j = 0; j < 4; ++j) q += v0[j] * v0[j] + v1[j] * v1[j]; }
;                     u32x4 w; w.x = cvt_pk_bf16(v0[0], v0[1]); w.y = cvt_pk_bf16(v0[2], v0[3]); w.z = cvt_pk_bf16(v1[0], v1[1]); w.w = cvt_pk_bf16(v1[2], v1[3]);
;                     __builtin_nontemporal_store(w, (u32x4*)(rowp + bj * HALF)); }
.LBB0_1091:
	s_lshl_b32 s17, s24, 8
	s_add_i32 s17, s17, s44
	v_mbcnt_lo_u32_b32 v138, -1, 0
	v_mbcnt_hi_u32_b32 v138, -1, v138
	s_nop 0
	v_and_or_b32 v150, v138, 15, s17
	v_ashrrev_i32_e32 v151, 31, v150
	v_lshl_add_u64 v[140:141], v[150:151], 2, s[12:13]
	v_lshrrev_b32_e32 v145, 1, v138
	s_lshl_b32 s17, s25, 8
	v_and_or_b32 v140, v145, 24, s17
	v_or_b32_e32 v140, s45, v140
	v_ashrrev_i32_e32 v141, 31, v140
	v_lshlrev_b64 v[154:155], 14, v[150:151]
	v_lshl_add_u64 v[160:161], s[8:9], 0, v[154:155]
	v_lshlrev_b64 v[154:155], 1, v[140:141]
	v_lshl_add_u64 v[140:141], v[160:161], 0, v[154:155]
	s_mov_b32 s17, 0x200000
	s_mov_b64 s[24:25], 0x200000
	v_pk_mul_f32 v[120:121], v[120:121], v[220:221] op_sel_hi:[1,0]
	v_pk_mul_f32 v[124:125], v[124:125], v[220:221] op_sel_hi:[1,0]
	v_pk_mul_f32 v[122:123], v[122:123], v[220:221] op_sel_hi:[1,0]
	v_max_f32_e32 v120, 0, v120
	v_pk_mul_f32 v[126:127], v[126:127], v[220:221] op_sel_hi:[1,0]
	v_mul_f32_e32 v145, v120, v120
	v_max_f32_e32 v120, 0, v125
	v_max_f32_e32 v121, 0, v121
	v_max_f32_e32 v122, 0, v122
	v_max_f32_e32 v124, 0, v124
	v_mul_f32_e32 v120, v120, v120
	v_mul_f32_e32 v125, v121, v121
	v_max_f32_e32 v121, 0, v126
	v_mul_f32_e32 v126, v122, v122
	v_max_f32_e32 v122, 0, v127
	v_max_f32_e32 v123, 0, v123
	v_pk_mul_f32 v[112:113], v[112:113], v[220:221] op_sel_hi:[1,0]
	v_mul_f32_e32 v124, v124, v124
	v_mul_f32_e32 v121, v121, v121
	v_mul_f32_e32 v122, v122, v122
	v_mul_f32_e32 v123, v123, v123
	v_cvt_pk_bf16_f32 v120, v124, v120
	v_pk_mul_f32 v[116:117], v[116:117], v[220:221] op_sel_hi:[1,0]
	v_pk_mul_f32 v[114:115], v[114:115], v[220:221] op_sel_hi:[1,0]
	v_max_f32_e32 v112, 0, v112
	v_cvt_pk_bf16_f32 v121, v121, v122
	v_cvt_pk_bf16_f32 v122, v145, v125
	v_cvt_pk_bf16_f32 v123, v126, v123
	global_store_dwordx4 v[140:141], v[120:123], off nt
	v_pk_mul_f32 v[118:119], v[118:119], v[220:221] op_sel_hi:[1,0]
	v_max_f32_e32 v113, 0, v113
	v_mul_f32_e32 v120, v112, v112
	v_max_f32_e32 v112, 0, v117
	v_max_f32_e32 v114, 0, v114
	v_max_f32_e32 v116, 0, v116
	v_mul_f32_e32 v112, v112, v112
	v_mul_f32_e32 v117, v113, v113
	v_max_f32_e32 v113, 0, v118
	v_mul_f32_e32 v118, v114, v114
	v_max_f32_e32 v114, 0, v119
	v_max_f32_e32 v115, 0, v115
	v_mul_f32_e32 v116, v116, v116
	v_mul_f32_e32 v113, v113, v113
	v_mul_f32_e32 v114, v114, v114
	v_mul_f32_e32 v115, v115, v115
	v_cvt_pk_bf16_f32 v112, v116, v112
	v_cvt_pk_bf16_f32 v113, v113, v114
	v_cvt_pk_bf16_f32 v114, v120, v117
	v_cvt_pk_bf16_f32 v115, v118, v115
	global_store_dwordx4 v[140:141], v[112:115], off offset:256 nt
	v_pk_mul_f32 v[104:105], v[104:105], v[228:229] op_sel_hi:[1,0]
	v_pk_mul_f32 v[108:109], v[108:109], v[228:229] op_sel_hi:[1,0]
	v_or_b32_e32 v112, 16, v150
	v_ashrrev_i32_e32 v113, 31, v112
	v_pk_mul_f32 v[106:107], v[106:107], v[228:229] op_sel_hi:[1,0]
	v_max_f32_e32 v104, 0, v104
	v_lshlrev_b64 v[112:113], 14, v[112:113]
	v_pk_mul_f32 v[110:111], v[110:111], v[228:229] op_sel_hi:[1,0]
	v_mul_f32_e32 v114, v104, v104
	v_max_f32_e32 v104, 0, v109
	v_max_f32_e32 v105, 0, v105
	v_max_f32_e32 v106, 0, v106
	v_lshl_add_u64 v[112:113], s[8:9], 0, v[112:113]
	v_max_f32_e32 v108, 0, v108
	v_mul_f32_e32 v104, v104, v104
	v_mul_f32_e32 v109, v105, v105
	v_max_f32_e32 v105, 0, v110
	v_mul_f32_e32 v110, v106, v106
	v_max_f32_e32 v106, 0, v111
	v_max_f32_e32 v107, 0, v107
	v_pk_mul_f32 v[96:97], v[96:97], v[228:229] op_sel_hi:[1,0]
	v_lshl_add_u64 v[112:113], v[112:113], 0, v[154:155]
	v_mul_f32_e32 v108, v108, v108
	v_mul_f32_e32 v105, v105, v105
	v_mul_f32_e32 v106, v106, v106
	v_mul_f32_e32 v107, v107, v107
	v_cvt_pk_bf16_f32 v104, v108, v104
	v_pk_mul_f32 v[100:101], v[100:101], v[228:229] op_sel_hi:[1,0]
	v_pk_mul_f32 v[98:99], v[98:99], v[228:229] op_sel_hi:[1,0]
	v_max_f32_e32 v96, 0, v96
	v_cvt_pk_bf16_f32 v105, v105, v106
	v_cvt_pk_bf16_f32 v106, v114, v109
	v_cvt_pk_bf16_f32 v107, v110, v107
	global_store_dwordx4 v[112:113], v[104:107], off nt
	v_pk_mul_f32 v[102:103], v[102:103], v[228:229] op_sel_hi:[1,0]
	v_max_f32_e32 v97, 0, v97
	v_mul_f32_e32 v104, v96, v96
	v_max_f32_e32 v96, 0, v101
	v_max_f32_e32 v98, 0, v98
	v_max_f32_e32 v100, 0, v100
	v_mul_f32_e32 v96, v96, v96
	v_mul_f32_e32 v101, v97, v97
	v_max_f32_e32 v97, 0, v102
	v_mul_f32_e32 v102, v98, v98
	v_max_f32_e32 v98, 0, v103
	v_max_f32_e32 v99, 0, v99
	v_mul_f32_e32 v100, v100, v100
	v_mul_f32_e32 v97, v97, v97
	v_mul_f32_e32 v98, v98, v98
	v_mul_f32_e32 v99, v99, v99
	v_cvt_pk_bf16_f32 v96, v100, v96
	v_cvt_pk_bf16_f32 v97, v97, v98
	v_cvt_pk_bf16_f32 v98, v104, v101
	v_cvt_pk_bf16_f32 v99, v102, v99
	global_store_dwordx4 v[112:113], v[96:99], off offset:256 nt
	v_pk_mul_f32 v[88:89], v[88:89], v[230:231] op_sel_hi:[1,0]
	v_pk_mul_f32 v[92:93], v[92:93], v[230:231] op_sel_hi:[1,0]
	v_or_b32_e32 v96, 32, v150
	v_ashrrev_i32_e32 v97, 31, v96
	v_pk_mul_f32 v[90:91], v[90:91], v[230:231] op_sel_hi:[1,0]
	v_max_f32_e32 v88, 0, v88
	v_lshlrev_b64 v[96:97], 14, v[96:97]
	v_pk_mul_f32 v[94:95], v[94:95], v[230:231] op_sel_hi:[1,0]
	v_mul_f32_e32 v98, v88, v88
	v_max_f32_e32 v88, 0, v93
	v_max_f32_e32 v89, 0, v89
	v_max_f32_e32 v90, 0, v90
	v_lshl_add_u64 v[96:97], s[8:9], 0, v[96:97]
	v_max_f32_e32 v92, 0, v92
	v_mul_f32_e32 v88, v88, v88
	v_mul_f32_e32 v93, v89, v89
	v_max_f32_e32 v89, 0, v94
	v_mul_f32_e32 v94, v90, v90
	v_max_f32_e32 v90, 0, v95
	v_max_f32_e32 v91, 0, v91
	v_pk_mul_f32 v[80:81], v[80:81], v[230:231] op_sel_hi:[1,0]
	v_lshl_add_u64 v[96:97], v[96:97], 0, v[154:155]
	v_mul_f32_e32 v92, v92, v92
	v_mul_f32_e32 v89, v89, v89
	v_mul_f32_e32 v90, v90, v90
	v_mul_f32_e32 v91, v91, v91
	v_cvt_pk_bf16_f32 v88, v92, v88
	v_pk_mul_f32 v[84:85], v[84:85], v[230:231] op_sel_hi:[1,0]
; __device__ __forceinline__ unsigned cvt_pk_bf16(float lo, float hi) { unsigned r; asm volatile("v_cvt_pk_bf16_f32 %0, %1, %2" : "=v"(r) : "v"(lo), "v"(hi)); return r; }
;     __device__ __forceinline__ void operator()(const f32x4 (&acc)[2][2][4][2], const Unit& u, int wr, int wc, int fr, int fq) const {
;     ...
;             for (int m = 0; m < 4; ++m) { const int row = row0 + ai * HALF + m * 16; bf16_t* rowp = O + (size_t)row * ldc + col0;
;                 const float sc = scr[ai * 4 + m];
;                 float q = 0.f;
; #pragma unroll
;                 for (int bj = 0; bj < 2; ++bj) { f32x4 v0 = acc[ai][bj][m][0], v1 = acc[ai][bj][m][1];
;                     if (RS) { v0 = v0 * sc; v1 = v1 * sc; }
;                     if (ACT == 1) {
; #pragma unroll
;                         for (int j = 0; j < 4; ++j) { const float a = fmaxf(v0[j], 0.f), b = fmaxf(v1[j], 0.f); v0[j] = a * a; v1[j] = b * b; } }
;                     if (SS) {
; #pragma unroll
;                         for (int j = 0; j < 4; ++j) q += v0[j] * v0[j] + v1[j] * v1[j]; }
;                     u32x4 w; w.x = cvt_pk_bf16(v0[0], v0[1]); w.y = cvt_pk_bf16(v0[2], v0[3]); w.z = cvt_pk_bf16(v1[0], v1[1]); w.w = cvt_pk_bf16(v1[2], v1[3]);
;                     __builtin_nontemporal_store(w, (u32x4*)(rowp + bj * HALF)); }
	v_pk_mul_f32 v[82:83], v[82:83], v[230:231] op_sel_hi:[1,0]
	v_max_f32_e32 v80, 0, v80
	v_cvt_pk_bf16_f32 v89, v89, v90
	v_cvt_pk_bf16_f32 v90, v98, v93
	v_cvt_pk_bf16_f32 v91, v94, v91
	global_store_dwordx4 v[96:97], v[88:91], off nt
	v_pk_mul_f32 v[86:87], v[86:87], v[230:231] op_sel_hi:[1,0]
	v_max_f32_e32 v81, 0, v81
	v_mul_f32_e32 v88, v80, v80
	v_max_f32_e32 v80, 0, v85
	v_max_f32_e32 v82, 0, v82
	v_max_f32_e32 v84, 0, v84
	v_mul_f32_e32 v80, v80, v80
	v_mul_f32_e32 v85, v81, v81
	v_max_f32_e32 v81, 0, v86
	v_mul_f32_e32 v86, v82, v82
	v_max_f32_e32 v82, 0, v87
	v_max_f32_e32 v83, 0, v83
	v_mul_f32_e32 v84, v84, v84
	v_mul_f32_e32 v81, v81, v81
	v_mul_f32_e32 v82, v82, v82
	v_mul_f32_e32 v83, v83, v83
	v_cvt_pk_bf16_f32 v80, v84, v80
	v_cvt_pk_bf16_f32 v81, v81, v82
	v_cvt_pk_bf16_f32 v82, v88, v85
	v_cvt_pk_bf16_f32 v83, v86, v83
	global_store_dwordx4 v[96:97], v[80:83], off offset:256 nt
	v_pk_mul_f32 v[72:73], v[72:73], v[232:233] op_sel_hi:[1,0]
	v_pk_mul_f32 v[76:77], v[76:77], v[232:233] op_sel_hi:[1,0]
	v_or_b32_e32 v80, 48, v150
	v_ashrrev_i32_e32 v81, 31, v80
	v_pk_mul_f32 v[74:75], v[74:75], v[232:233] op_sel_hi:[1,0]
	v_max_f32_e32 v72, 0, v72
	v_lshlrev_b64 v[80:81], 14, v[80:81]
	v_pk_mul_f32 v[78:79], v[78:79], v[232:233] op_sel_hi:[1,0]
	v_mul_f32_e32 v82, v72, v72
	v_max_f32_e32 v72, 0, v77
	v_max_f32_e32 v73, 0, v73
	v_max_f32_e32 v74, 0, v74
	v_lshl_add_u64 v[80:81], s[8:9], 0, v[80:81]
	v_max_f32_e32 v76, 0, v76
	v_mul_f32_e32 v72, v72, v72
	v_mul_f32_e32 v77, v73, v73
	v_max_f32_e32 v73, 0, v78
	v_mul_f32_e32 v78, v74, v74
	v_max_f32_e32 v74, 0, v79
	v_max_f32_e32 v75, 0, v75
	v_pk_mul_f32 v[66:67], v[66:67], v[232:233] op_sel_hi:[1,0]
	v_pk_mul_f32 v[64:65], v[64:65], v[232:233] op_sel_hi:[1,0]
	v_lshl_add_u64 v[80:81], v[80:81], 0, v[154:155]
	v_mul_f32_e32 v76, v76, v76
	v_mul_f32_e32 v73, v73, v73
	v_mul_f32_e32 v74, v74, v74
	v_mul_f32_e32 v75, v75, v75
	v_cvt_pk_bf16_f32 v72, v76, v72
	v_pk_mul_f32 v[70:71], v[70:71], v[232:233] op_sel_hi:[1,0]
	v_pk_mul_f32 v[68:69], v[68:69], v[232:233] op_sel_hi:[1,0]
	v_max_f32_e32 v64, 0, v64
	v_max_f32_e32 v65, 0, v65
	v_max_f32_e32 v66, 0, v66
	v_cvt_pk_bf16_f32 v73, v73, v74
	v_cvt_pk_bf16_f32 v74, v82, v77
	v_cvt_pk_bf16_f32 v75, v78, v75
	global_store_dwordx4 v[80:81], v[72:75], off nt
	v_max_f32_e32 v68, 0, v68
	v_max_f32_e32 v67, 0, v67
	v_mul_f32_e32 v72, v64, v64
	v_max_f32_e32 v64, 0, v69
	v_mul_f32_e32 v69, v65, v65
	v_max_f32_e32 v65, 0, v70
	v_mul_f32_e32 v70, v66, v66
	v_max_f32_e32 v66, 0, v71
	v_mul_f32_e32 v64, v64, v64
	v_mul_f32_e32 v65, v65, v65
	v_mul_f32_e32 v66, v66, v66
	v_pk_mul_f32 v[56:57], v[56:57], v[236:237] op_sel_hi:[1,0]
	v_mul_f32_e32 v68, v68, v68
	v_mul_f32_e32 v67, v67, v67
	v_cvt_pk_bf16_f32 v64, v68, v64
	v_cvt_pk_bf16_f32 v65, v65, v66
	v_cvt_pk_bf16_f32 v66, v72, v69
	v_pk_mul_f32 v[60:61], v[60:61], v[236:237] op_sel_hi:[1,0]
	v_pk_mul_f32 v[58:59], v[58:59], v[236:237] op_sel_hi:[1,0]
	v_max_f32_e32 v56, 0, v56
	v_cvt_pk_bf16_f32 v67, v70, v67
	global_store_dwordx4 v[80:81], v[64:67], off offset:256 nt
	v_pk_mul_f32 v[62:63], v[62:63], v[236:237] op_sel_hi:[1,0]
	v_max_f32_e32 v60, 0, v60
	v_mul_f32_e32 v66, v56, v56
	v_max_f32_e32 v56, 0, v61
	v_max_f32_e32 v57, 0, v57
	v_max_f32_e32 v58, 0, v58
	v_mul_f32_e32 v60, v60, v60
	v_mul_f32_e32 v56, v56, v56
	v_mul_f32_e32 v61, v57, v57
	v_max_f32_e32 v57, 0, v62
	v_mul_f32_e32 v62, v58, v58
	v_max_f32_e32 v58, 0, v63
	v_mul_f32_e32 v57, v57, v57
	v_max_f32_e32 v59, 0, v59
	v_mul_f32_e32 v58, v58, v58
	v_cvt_pk_bf16_f32 v56, v60, v56
	v_add_co_u32_e32 v60, vcc, s17, v140
	v_pk_mul_f32 v[50:51], v[50:51], v[236:237] op_sel_hi:[1,0]
	v_pk_mul_f32 v[48:49], v[48:49], v[236:237] op_sel_hi:[1,0]
	v_mul_f32_e32 v59, v59, v59
	v_cvt_pk_bf16_f32 v57, v57, v58
	v_cvt_pk_bf16_f32 v58, v66, v61
	v_addc_co_u32_e32 v61, vcc, 0, v141, vcc
	v_pk_mul_f32 v[54:55], v[54:55], v[236:237] op_sel_hi:[1,0]
	v_pk_mul_f32 v[52:53], v[52:53], v[236:237] op_sel_hi:[1,0]
	v_max_f32_e32 v48, 0, v48
	v_max_f32_e32 v49, 0, v49
	v_max_f32_e32 v50, 0, v50
	v_cvt_pk_bf16_f32 v59, v62, v59
	global_store_dwordx4 v[60:61], v[56:59], off nt
	v_max_f32_e32 v52, 0, v52
	v_max_f32_e32 v51, 0, v51
	v_mul_f32_e32 v56, v48, v48
	v_max_f32_e32 v48, 0, v53
	v_mul_f32_e32 v53, v49, v49
	v_max_f32_e32 v49, 0, v54
	v_mul_f32_e32 v54, v50, v50
	v_max_f32_e32 v50, 0, v55
	v_mul_f32_e32 v48, v48, v48
	v_mul_f32_e32 v49, v49, v49
	v_mul_f32_e32 v50, v50, v50
	v_pk_mul_f32 v[40:41], v[40:41], v[240:241] op_sel_hi:[1,0]
	v_lshl_add_u64 v[64:65], v[140:141], 0, s[24:25]
	v_mul_f32_e32 v52, v52, v52
	v_mul_f32_e32 v51, v51, v51
	v_cvt_pk_bf16_f32 v48, v52, v48
	v_cvt_pk_bf16_f32 v49, v49, v50
	v_cvt_pk_bf16_f32 v50, v56, v53
	v_pk_mul_f32 v[44:45], v[44:45], v[240:241] op_sel_hi:[1,0]
	v_pk_mul_f32 v[42:43], v[42:43], v[240:241] op_sel_hi:[1,0]
	v_max_f32_e32 v40, 0, v40
	v_cvt_pk_bf16_f32 v51, v54, v51
	global_store_dwordx4 v[64:65], v[48:51], off offset:256 nt
	v_pk_mul_f32 v[46:47], v[46:47], v[240:241] op_sel_hi:[1,0]
	v_max_f32_e32 v44, 0, v44
	v_mul_f32_e32 v50, v40, v40
	v_max_f32_e32 v40, 0, v45
	v_max_f32_e32 v41, 0, v41
	v_max_f32_e32 v42, 0, v42
	v_mul_f32_e32 v44, v44, v44
	v_mul_f32_e32 v40, v40, v40
	v_mul_f32_e32 v45, v41, v41
	v_max_f32_e32 v41, 0, v46
	v_mul_f32_e32 v46, v42, v42
	v_max_f32_e32 v42, 0, v47
; __device__ __forceinline__ unsigned cvt_pk_bf16(float lo, float hi) { unsigned r; asm volatile("v_cvt_pk_bf16_f32 %0, %1, %2" : "=v"(r) : "v"(lo), "v"(hi)); return r; }
; #define PG8_BAR __builtin_amdgcn_s_barrier()
;     __device__ __forceinline__ void operator()(const f32x4 (&acc)[2][2][4][2], const Unit& u, int wr, int wc, int fr, int fq) const {
;     ...
;             for (int m = 0; m < 4; ++m) { const int row = row0 + ai * HALF + m * 16; bf16_t* rowp = O + (size_t)row * ldc + col0;
;                 const float sc = scr[ai * 4 + m];
;                 float q = 0.f;
; #pragma unroll
;                 for (int bj = 0; bj < 2; ++bj) { f32x4 v0 = acc[ai][bj][m][0], v1 = acc[ai][bj][m][1];
;                     if (RS) { v0 = v0 * sc; v1 = v1 * sc; }
;                     if (ACT == 1) {
; #pragma unroll
;                         for (int j = 0; j < 4; ++j) { const float a = fmaxf(v0[j], 0.f), b = fmaxf(v1[j], 0.f); v0[j] = a * a; v1[j] = b * b; } }
;                     if (SS) {
; #pragma unroll
;                         for (int j = 0; j < 4; ++j) q += v0[j] * v0[j] + v1[j] * v1[j]; }
;                     u32x4 w; w.x = cvt_pk_bf16(v0[0], v0[1]); w.y = cvt_pk_bf16(v0[2], v0[3]); w.z = cvt_pk_bf16(v1[0], v1[1]); w.w = cvt_pk_bf16(v1[2], v1[3]);
;                     __builtin_nontemporal_store(w, (u32x4*)(rowp + bj * HALF)); }
; template <class Epi, class Sched, bool ALIGN_EPI = false, bool SP2 = false>
; __device__ __forceinline__ void gemm_phase(PG8_LAS unsigned char* lds, const Gemm g, const Sched& S, const Epi& E, const int tid) {
;     ...
;         if (!has_next) break;
;         if constexpr (!Epi::ACC_INIT) {
; #pragma unroll
;         for (int a = 0; a < 2; ++a)
; #pragma unroll
;             for (int b = 0; b < 2; ++b)
; #pragma unroll
;                 for (int m = 0; m < 4; ++m)
; #pragma unroll
;                     for (int n = 0; n < 2; ++n) acc[a][b][m][n] = (f32x4){0.f, 0.f, 0.f, 0.f};
;         }
;         cur = nxt; cA = nA; cB = nB; ++ui;
;         if constexpr (ALIGN_EPI) { if (wr == 1) PG8_BAR; }
	s_mov_b32 s17, 0x240000
	v_mul_f32_e32 v41, v41, v41
	v_max_f32_e32 v43, 0, v43
	v_mul_f32_e32 v42, v42, v42
	v_cvt_pk_bf16_f32 v40, v44, v40
	v_add_co_u32_e32 v44, vcc, s17, v140
	v_pk_mul_f32 v[34:35], v[34:35], v[240:241] op_sel_hi:[1,0]
	v_pk_mul_f32 v[32:33], v[32:33], v[240:241] op_sel_hi:[1,0]
	v_mul_f32_e32 v43, v43, v43
	v_cvt_pk_bf16_f32 v41, v41, v42
	v_cvt_pk_bf16_f32 v42, v50, v45
	v_addc_co_u32_e32 v45, vcc, 0, v141, vcc
	v_pk_mul_f32 v[38:39], v[38:39], v[240:241] op_sel_hi:[1,0]
	v_pk_mul_f32 v[36:37], v[36:37], v[240:241] op_sel_hi:[1,0]
	v_max_f32_e32 v32, 0, v32
	v_max_f32_e32 v33, 0, v33
	v_max_f32_e32 v34, 0, v34
	v_cvt_pk_bf16_f32 v43, v46, v43
	global_store_dwordx4 v[44:45], v[40:43], off nt
	s_mov_b64 s[24:25], 0x240000
	v_max_f32_e32 v36, 0, v36
	v_mul_f32_e32 v40, v32, v32
	v_max_f32_e32 v32, 0, v37
	v_mul_f32_e32 v37, v33, v33
	v_max_f32_e32 v33, 0, v38
	v_mul_f32_e32 v38, v34, v34
	v_max_f32_e32 v34, 0, v39
	v_mul_f32_e32 v32, v32, v32
	v_mul_f32_e32 v33, v33, v33
	v_max_f32_e32 v35, 0, v35
	v_mul_f32_e32 v34, v34, v34
	v_pk_mul_f32 v[24:25], v[24:25], v[242:243] op_sel_hi:[1,0]
	v_lshl_add_u64 v[48:49], v[140:141], 0, s[24:25]
	v_mul_f32_e32 v36, v36, v36
	v_mul_f32_e32 v35, v35, v35
	v_cvt_pk_bf16_f32 v32, v36, v32
	v_cvt_pk_bf16_f32 v33, v33, v34
	v_cvt_pk_bf16_f32 v34, v40, v37
	v_pk_mul_f32 v[28:29], v[28:29], v[242:243] op_sel_hi:[1,0]
	v_pk_mul_f32 v[26:27], v[26:27], v[242:243] op_sel_hi:[1,0]
	v_max_f32_e32 v24, 0, v24
	v_cvt_pk_bf16_f32 v35, v38, v35
	global_store_dwordx4 v[48:49], v[32:35], off offset:256 nt
	v_pk_mul_f32 v[30:31], v[30:31], v[242:243] op_sel_hi:[1,0]
	v_max_f32_e32 v28, 0, v28
	v_mul_f32_e32 v34, v24, v24
	v_max_f32_e32 v24, 0, v29
	v_max_f32_e32 v25, 0, v25
	v_max_f32_e32 v26, 0, v26
	v_mul_f32_e32 v28, v28, v28
	v_mul_f32_e32 v24, v24, v24
	v_mul_f32_e32 v29, v25, v25
	v_max_f32_e32 v25, 0, v30
	v_mul_f32_e32 v30, v26, v26
	v_max_f32_e32 v26, 0, v31
	s_mov_b32 s17, 0x280000
	v_mul_f32_e32 v25, v25, v25
	v_max_f32_e32 v27, 0, v27
	v_mul_f32_e32 v26, v26, v26
	v_cvt_pk_bf16_f32 v24, v28, v24
	v_add_co_u32_e32 v28, vcc, s17, v140
	v_pk_mul_f32 v[18:19], v[18:19], v[242:243] op_sel_hi:[1,0]
	v_pk_mul_f32 v[16:17], v[16:17], v[242:243] op_sel_hi:[1,0]
	v_mul_f32_e32 v27, v27, v27
	v_cvt_pk_bf16_f32 v25, v25, v26
	v_cvt_pk_bf16_f32 v26, v34, v29
	v_addc_co_u32_e32 v29, vcc, 0, v141, vcc
	v_pk_mul_f32 v[22:23], v[22:23], v[242:243] op_sel_hi:[1,0]
	v_pk_mul_f32 v[20:21], v[20:21], v[242:243] op_sel_hi:[1,0]
	v_max_f32_e32 v16, 0, v16
	v_max_f32_e32 v17, 0, v17
	v_max_f32_e32 v18, 0, v18
	v_cvt_pk_bf16_f32 v27, v30, v27
	global_store_dwordx4 v[28:29], v[24:27], off nt
	s_mov_b64 s[24:25], 0x280000
	v_max_f32_e32 v20, 0, v20
	v_mul_f32_e32 v24, v16, v16
	v_max_f32_e32 v16, 0, v21
	v_mul_f32_e32 v21, v17, v17
	v_max_f32_e32 v17, 0, v22
	v_mul_f32_e32 v22, v18, v18
	v_max_f32_e32 v18, 0, v23
	v_mul_f32_e32 v16, v16, v16
	v_mul_f32_e32 v17, v17, v17
	v_max_f32_e32 v19, 0, v19
	v_mul_f32_e32 v18, v18, v18
	v_pk_mul_f32 v[8:9], v[8:9], v[244:245] op_sel_hi:[1,0]
	v_lshl_add_u64 v[32:33], v[140:141], 0, s[24:25]
	v_mul_f32_e32 v20, v20, v20
	v_mul_f32_e32 v19, v19, v19
	v_cvt_pk_bf16_f32 v16, v20, v16
	v_cvt_pk_bf16_f32 v17, v17, v18
	v_cvt_pk_bf16_f32 v18, v24, v21
	v_pk_mul_f32 v[12:13], v[12:13], v[244:245] op_sel_hi:[1,0]
	v_pk_mul_f32 v[10:11], v[10:11], v[244:245] op_sel_hi:[1,0]
	v_max_f32_e32 v8, 0, v8
	v_cvt_pk_bf16_f32 v19, v22, v19
	global_store_dwordx4 v[32:33], v[16:19], off offset:256 nt
	v_pk_mul_f32 v[14:15], v[14:15], v[244:245] op_sel_hi:[1,0]
	v_max_f32_e32 v12, 0, v12
	v_mul_f32_e32 v18, v8, v8
	v_max_f32_e32 v8, 0, v13
	v_max_f32_e32 v9, 0, v9
	v_max_f32_e32 v10, 0, v10
	v_mul_f32_e32 v12, v12, v12
	v_mul_f32_e32 v8, v8, v8
	v_mul_f32_e32 v13, v9, v9
	v_max_f32_e32 v9, 0, v14
	v_mul_f32_e32 v14, v10, v10
	v_max_f32_e32 v10, 0, v15
	s_mov_b32 s17, 0x2c0000
	v_mul_f32_e32 v9, v9, v9
	v_max_f32_e32 v11, 0, v11
	v_mul_f32_e32 v10, v10, v10
	v_cvt_pk_bf16_f32 v8, v12, v8
	v_add_co_u32_e32 v12, vcc, s17, v140
	v_pk_mul_f32 v[2:3], v[2:3], v[244:245] op_sel_hi:[1,0]
	v_pk_mul_f32 v[0:1], v[0:1], v[244:245] op_sel_hi:[1,0]
	v_mul_f32_e32 v11, v11, v11
	v_cvt_pk_bf16_f32 v9, v9, v10
	v_cvt_pk_bf16_f32 v10, v18, v13
	v_addc_co_u32_e32 v13, vcc, 0, v141, vcc
	v_pk_mul_f32 v[6:7], v[6:7], v[244:245] op_sel_hi:[1,0]
	v_pk_mul_f32 v[4:5], v[4:5], v[244:245] op_sel_hi:[1,0]
	v_max_f32_e32 v0, 0, v0
	v_max_f32_e32 v1, 0, v1
	v_max_f32_e32 v2, 0, v2
	s_mov_b64 s[24:25], 0x2c0000
	v_cvt_pk_bf16_f32 v11, v14, v11
	global_store_dwordx4 v[12:13], v[8:11], off nt
	v_max_f32_e32 v3, 0, v3
	v_lshl_add_u64 v[16:17], v[140:141], 0, s[24:25]
	v_mul_f32_e32 v8, v0, v0
	v_max_f32_e32 v0, 0, v5
	v_mul_f32_e32 v5, v1, v1
	v_max_f32_e32 v1, 0, v6
	v_mul_f32_e32 v6, v2, v2
	v_max_f32_e32 v2, 0, v7
	v_max_f32_e32 v4, 0, v4
	v_mul_f32_e32 v0, v0, v0
	v_mul_f32_e32 v1, v1, v1
	v_mul_f32_e32 v2, v2, v2
	v_mul_f32_e32 v3, v3, v3
	s_mov_b64 s[24:25], -1
	s_andn2_b64 vcc, exec, s[4:5]
	v_mul_f32_e32 v4, v4, v4
	v_cvt_pk_bf16_f32 v0, v4, v0
	v_cvt_pk_bf16_f32 v1, v1, v2
	v_cvt_pk_bf16_f32 v2, v8, v5
	v_cvt_pk_bf16_f32 v3, v6, v3
	global_store_dwordx4 v[16:17], v[0:3], off offset:256 nt
	s_cbranch_vccnz .LBB0_1080
	s_andn2_b64 vcc, exec, s[6:7]
	s_cbranch_vccnz .LBB0_1079
	s_barrier
	s_branch .LBB0_1079

; __global__ void __launch_bounds__(NWAVES * 64, 2) mk_fwd(Args args) {
	.amdhsa_kernel _Z6mk_fwd4Args
		.amdhsa_group_segment_fixed_size 0
		.amdhsa_private_segment_fixed_size 0
		.amdhsa_kernarg_size 496
		.amdhsa_user_sgpr_count 2
		.amdhsa_user_sgpr_dispatch_ptr 0
		.amdhsa_user_sgpr_queue_ptr 0
		.amdhsa_user_sgpr_kernarg_segment_ptr 1
		.amdhsa_user_sgpr_dispatch_id 0
		.amdhsa_user_sgpr_kernarg_preload_length 0
		.amdhsa_user_sgpr_kernarg_preload_offset 0
		.amdhsa_user_sgpr_private_segment_size 0
		.amdhsa_uses_dynamic_stack 0
		.amdhsa_enable_private_segment 0
		.amdhsa_system_sgpr_workgroup_id_x 1
		.amdhsa_system_sgpr_workgroup_id_y 0
		.amdhsa_system_sgpr_workgroup_id_z 0
		.amdhsa_system_sgpr_workgroup_info 0
		.amdhsa_system_vgpr_workitem_id 0
		.amdhsa_next_free_vgpr 256
		.amdhsa_next_free_sgpr 102
		.amdhsa_accum_offset 256
		.amdhsa_reserve_vcc 1
		.amdhsa_float_round_mode_32 0
		.amdhsa_float_round_mode_16_64 0
		.amdhsa_float_denorm_mode_32 3
		.amdhsa_float_denorm_mode_16_64 3
		.amdhsa_dx10_clamp 1
		.amdhsa_ieee_mode 1
		.amdhsa_fp16_overflow 0
		.amdhsa_tg_split 0
		.amdhsa_exception_fp_ieee_invalid_op 0
		.amdhsa_exception_fp_denorm_src 0
		.amdhsa_exception_fp_ieee_div_zero 0
		.amdhsa_exception_fp_ieee_overflow 0
		.amdhsa_exception_fp_ieee_underflow 0
		.amdhsa_exception_fp_ieee_inexact 0
		.amdhsa_exception_int_div_zero 0
	.end_amdhsa_kernel

; __global__ void __launch_bounds__(NWAVES * 64, 2) mk_fwd(Args args) {
amdhsa.kernels:
  - .agpr_count:     0
    .args:
      - .offset:         0
        .size:           240
        .value_kind:     by_value
      - .offset:         240
        .size:           4
        .value_kind:     hidden_block_count_x
      - .offset:         244
        .size:           4
        .value_kind:     hidden_block_count_y
      - .offset:         248
        .size:           4
        .value_kind:     hidden_block_count_z
      - .offset:         252
        .size:           2
        .value_kind:     hidden_group_size_x
      - .offset:         254
        .size:           2
        .value_kind:     hidden_group_size_y
      - .offset:         256
        .size:           2
        .value_kind:     hidden_group_size_z
      - .offset:         258
        .size:           2
        .value_kind:     hidden_remainder_x
      - .offset:         260
        .size:           2
        .value_kind:     hidden_remainder_y
      - .offset:         262
        .size:           2
        .value_kind:     hidden_remainder_z
      - .offset:         280
        .size:           8
        .value_kind:     hidden_global_offset_x
      - .offset:         288
        .size:           8
        .value_kind:     hidden_global_offset_y
      - .offset:         296
        .size:           8
        .value_kind:     hidden_global_offset_z
      - .offset:         304
        .size:           2
        .value_kind:     hidden_grid_dims
      - .offset:         360
        .size:           4
        .value_kind:     hidden_dynamic_lds_size
    .group_segment_fixed_size: 0
    .kernarg_segment_align: 8
    .kernarg_segment_size: 496
    .language:       OpenCL C
    .language_version:
      - 2
      - 0
    .max_flat_workgroup_size: 512
    .name:           _Z6mk_fwd4Args
    .private_segment_fixed_size: 0
    .sgpr_count:     108
    .sgpr_spill_count: 25
    .symbol:         _Z6mk_fwd4Args.kd
    .uniform_work_group_size: 1
    .uses_dynamic_stack: false
    .vgpr_count:     256
    .vgpr_spill_count: 0
    .wavefront_size: 64
